# cache policy: nt on NSA's read-once query-tile loads
# baseline (speedup 1.0000x reference)
; #define LAS __attribute__((address_space(3)))
; #define MFMA32(a, b, c) __builtin_amdgcn_mfma_f32_32x32x16_bf16((a), (b), (c), 0, 0, 0)
; __device__ __forceinline__ void nsa_unit(const Frame& F, int plane, int qt) {
;     LAS unsigned char* L = F.lds;
;     const int lane = F.lane, r = lane & 31, h = lane >> 5, w = F.wave;
;     const int b = plane >> 1, kvh = plane & 1, g = r & 3, head = kvh * 4 + g;
;     const int t = qt * 64 + w * 8 + (r >> 2), cur = qt;
;     const size_t tok = (size_t)b * S + t;
;     const size_t qoff = (((size_t)b * 8 + head) * S + t) * 64 + 8 * h;
;     const float* ng = (const float*)(F.ws + WS_NG) + tok * 24 + head * 3;
;     const float gate_c = ng[0], gate_s = ng[1], gate_w = ng[2];
;     unsigned selmask = 0u;
;     __syncthreads();
;     { const int row = F.tid >> 2, part = F.tid & 3;
;       const u32x4* src = (const u32x4*)((const bf16*)(F.ws + WS_KCB) + ((size_t)plane * 128 + row) * 64 + part * 16);
;       *(LAS u32x4*)(L + NL_KC + row * 144 + part * 32) = src[0]; *(LAS u32x4*)(L + NL_KC + row * 144 + part * 32 + 16) = src[1];
;       const int d = F.tid >> 3, p8 = F.tid & 7;
;       const u32x4* sv = (const u32x4*)((const bf16*)(F.ws + WS_VCT) + ((size_t)plane * 64 + d) * 128 + p8 * 16);
;       *(LAS u32x4*)(L + NL_VC + d * 272 + p8 * 32) = sv[0]; *(LAS u32x4*)(L + NL_VC + d * 272 + p8 * 32 + 16) = sv[1]; }
;     __syncthreads();
;     {
;         bf16x8 qu[4];
; #pragma unroll
;         for (int ks = 0; ks < 4; ++ks) qu[ks] = *(const bf16x8*)((const bf16*)(F.ws + WS_NQU) + qoff + 16 * ks);
;         const int cmax = (t - 31) >> 4;
;         float mx = -1e20f;
; #pragma unroll
;         for (int ct = 0; ct < 4; ++ct) {
;             f32x16 sc;
; #pragma unroll
;             for (int i = 0; i < 16; ++i) sc[i] = 0.f;
; #pragma unroll
;             for (int ks = 0; ks < 4; ++ks) { const bf16x8 a = *(const LAS bf16x8*)(L + NL_KC + (32 * ct + r) * 144 + (16 * ks + 8 * h) * 2); sc = MFMA32(a, qu[ks], sc); }
.LBB0_1751:
	v_mov_b32_e32 v1, v0
	v_readlane_b32 s40, v251, 0
	v_readlane_b32 s41, v251, 1
	v_readfirstlane_b32 s0, v1
	s_ashr_i32 s5, s0, 6
	s_mov_b64 s[28:29], s[78:79]
	s_mov_b64 s[0:1], s[40:41]
	s_and_b32 s3, s6, 15
	s_lshr_b32 s4, s6, 4
	s_bfe_u32 s9, s6, 0x40004
	s_xor_b32 s0, s3, 31
	s_cmpk_lt_i32 s6, 0x100
	s_cselect_b32 s8, s3, s0
	s_waitcnt vmcnt(0)
	v_and_b32_e32 v6, 3, v1
	s_lshr_b32 s1, s6, 2
	v_and_or_b32 v161, s1, 4, v6
	s_lshl_b32 s7, s8, 6
	s_lshl_b32 s1, s5, 3
	s_add_i32 s1, s1, s7
	s_waitcnt vmcnt(15)
	v_bfe_u32 v2, v1, 2, 3
	s_bfe_u32 s0, s4, 0x30001
	s_waitcnt vmcnt(2)
	v_or_b32_e32 v128, s1, v2
	s_lshl_b32 s34, s0, 11
	v_ashrrev_i32_e32 v129, 31, v128
	v_lshl_add_u64 v[126:127], s[34:35], 0, v[128:129]
	v_lshlrev_b32_e32 v2, 11, v161
	v_mov_b64_e32 v[4:5], s[28:29]
	s_movk_i32 s3, 0x60
	v_lshl_or_b32 v198, s0, 14, v2
	v_mad_u64_u32 v[4:5], s[0:1], v126, s3, v[4:5]
	v_mul_u32_u24_e32 v7, 3, v161
	v_lshl_add_u64 v[2:3], v[198:199], 0, v[128:129]
	v_mad_i32_i24 v5, v127, s3, v5
	v_lshlrev_b32_e32 v198, 2, v7
	v_lshl_add_u64 v[4:5], v[4:5], 0, v[198:199]
	s_mov_b32 s0, 0x6f000000
	v_add_co_u32_e32 v4, vcc, s0, v4
	v_ashrrev_i32_e32 v12, 2, v1
	s_lshl_b32 s0, s9, 14
	v_addc_co_u32_e32 v5, vcc, 0, v5, vcc
	v_ashrrev_i32_e32 v13, 31, v12
	s_add_u32 s0, s28, s0
	global_load_dwordx3 v[122:124], v[4:5], off
	v_lshlrev_b64 v[4:5], 7, v[12:13]
	s_addc_u32 s1, s29, 0
	v_lshl_add_u64 v[4:5], s[0:1], 0, v[4:5]
	v_lshlrev_b32_e32 v198, 5, v6
	v_lshl_add_u64 v[4:5], v[4:5], 0, v[198:199]
	s_mov_b64 s[10:11], 0x6fc00000
	s_mov_b32 s3, 0x6fc00000
	v_lshl_add_u64 v[8:9], v[4:5], 0, s[10:11]
	v_add_co_u32_e32 v4, vcc, s3, v4
	s_nop 1
	v_addc_co_u32_e32 v5, vcc, 0, v5, vcc
	s_barrier
	global_load_dwordx4 v[4:7], v[4:5], off
	s_nop 0
	global_load_dwordx4 v[8:11], v[8:9], off offset:16
	s_movk_i32 s10, 0x90
	v_mul_lo_u32 v12, v12, s10
	s_waitcnt vmcnt(4)
	v_ashrrev_i32_e32 v130, 3, v1
	v_add3_u32 v12, 0, v12, v198
	v_ashrrev_i32_e32 v131, 31, v130
	v_and_b32_e32 v114, 7, v1
	v_mov_b32_e32 v13, v199
	s_movk_i32 s11, 0x110
	v_and_b32_e32 v14, 63, v1
	v_and_b32_e32 v83, 31, v1
	v_bfe_u32 v1, v1, 5, 1
	v_lshlrev_b64 v[2:3], 6, v[2:3]
	v_lshlrev_b32_e32 v206, 3, v1
	v_or_b32_e32 v2, v2, v206
	s_waitcnt vmcnt(3)
	v_lshl_add_u64 v[66:67], v[2:3], 1, s[28:29]
	v_lshlrev_b32_e32 v97, 4, v1
	v_add_u32_e32 v19, 0, v97
	v_mad_u32_u24 v100, v83, s10, v19
	v_lshlrev_b32_e32 v204, 2, v1
	s_mov_b32 s14, 8
	v_lshlrev_b32_e32 v198, 4, v114
	v_mul_u32_u24_e32 v96, 0x90, v83
	s_movk_i32 s3, 0x90
	v_or_b32_e32 v68, 2, v1
	v_or_b32_e32 v69, 24, v1
	v_or_b32_e32 v70, 26, v1
	v_or_b32_e32 v71, 20, v1
	v_or_b32_e32 v72, 22, v1
	v_or_b32_e32 v73, 16, v1
	v_or_b32_e32 v74, 18, v1
	v_or_b32_e32 v75, 12, v1
	v_or_b32_e32 v76, 14, v1
	v_or_b32_e32 v77, 8, v1
	v_or_b32_e32 v78, 10, v1
	v_readlane_b32 s42, v251, 2
	v_readlane_b32 s43, v251, 3
	s_waitcnt vmcnt(1)
	ds_write_b128 v12, v[4:7]
	s_waitcnt vmcnt(0)
	ds_write_b128 v12, v[8:11] offset:16
	v_lshlrev_b64 v[4:5], 8, v[130:131]
	v_lshl_add_u64 v[4:5], s[0:1], 0, v[4:5]
	v_lshlrev_b32_e32 v12, 5, v114
	v_lshl_add_u64 v[4:5], v[4:5], 0, v[12:13]
	s_mov_b64 s[0:1], 0x6fd00000
	v_lshl_add_u64 v[8:9], v[4:5], 0, s[0:1]
	s_mov_b32 s0, 0x6fd00000
	v_add_co_u32_e32 v4, vcc, s0, v4
	v_mul_lo_u32 v13, v130, s11
	s_nop 0
	v_addc_co_u32_e32 v5, vcc, 0, v5, vcc
	global_load_dwordx4 v[4:7], v[4:5], off
	s_nop 0
	global_load_dwordx4 v[8:11], v[8:9], off offset:16
	v_add3_u32 v12, 0, v13, v12
	s_lshl_b32 s0, s5, 13
	s_add_i32 s0, s0, 0
	v_lshl_add_u32 v203, v14, 2, s0
	s_waitcnt vmcnt(1)
	ds_write_b128 v12, v[4:7] offset:18432
	s_waitcnt vmcnt(0)
	ds_write_b128 v12, v[8:11] offset:18448
	v_subrev_u32_e32 v4, 31, v128
	v_and_b32_e32 v5, 64, v225
	v_ashrrev_i32_e32 v18, 4, v4
	v_xor_b32_e32 v4, 32, v225
	v_add_u32_e32 v5, 64, v5
	v_cmp_lt_i32_e32 vcc, v4, v5
	s_waitcnt lgkmcnt(0)
	s_barrier
	v_cndmask_b32_e32 v4, v225, v4, vcc
	v_lshlrev_b32_e32 v205, 2, v4
	v_xor_b32_e32 v4, 1, v225
	v_cmp_lt_i32_e64 s[0:1], v4, v5
	v_cmp_gt_u32_e32 vcc, 32, v14
	s_nop 0
	v_cndmask_b32_e64 v4, v225, v4, s[0:1]
	v_lshlrev_b32_e32 v99, 2, v4
	v_xor_b32_e32 v4, 2, v225
	v_cmp_lt_i32_e64 s[0:1], v4, v5
	s_nop 1
	v_cndmask_b32_e64 v4, v225, v4, s[0:1]
	s_mov_b64 s[0:1], 0x6b800000
	v_lshl_add_u64 v[2:3], v[66:67], 0, s[0:1]
	s_mov_b32 s0, 0x6b800000
	v_lshlrev_b32_e32 v98, 2, v4
	v_add_co_u32_e64 v4, s[0:1], s0, v66
	s_nop 1
	v_addc_co_u32_e64 v5, s[0:1], 0, v67, s[0:1]
	global_load_dwordx4 v[58:61], v[4:5], off nt
	global_load_dwordx4 v[54:57], v[2:3], off offset:32 nt
	global_load_dwordx4 v[50:53], v[2:3], off offset:64 nt
	global_load_dwordx4 v[62:65], v[2:3], off offset:96 nt
	ds_read_b128 v[2:5], v100
	ds_read_b128 v[20:23], v100 offset:32
	v_cmp_lt_i32_e64 s[0:1], v18, v204
	s_waitcnt vmcnt(3) lgkmcnt(1)
	v_mfma_f32_32x32x16_bf16 v[2:17], v[2:5], v[58:61], 0
	ds_read_b128 v[36:39], v100 offset:4640
	s_waitcnt vmcnt(2) lgkmcnt(1)
	v_mfma_f32_32x32x16_bf16 v[2:17], v[20:23], v[54:57], v[2:17]
	ds_read_b128 v[20:23], v100 offset:64
	s_waitcnt vmcnt(1) lgkmcnt(0)
	v_mfma_f32_32x32x16_bf16 v[2:17], v[20:23], v[50:53], v[2:17]
	ds_read_b128 v[20:23], v100 offset:96
	s_waitcnt vmcnt(0) lgkmcnt(0)
; #define LAS __attribute__((address_space(3)))
; #define MFMA32(a, b, c) __builtin_amdgcn_mfma_f32_32x32x16_bf16((a), (b), (c), 0, 0, 0)
; __device__ __forceinline__ void nsa_unit(const Frame& F, int plane, int qt) {
;     ...
;         for (int ct = 0; ct < 4; ++ct) {
;             f32x16 sc;
; #pragma unroll
;             for (int i = 0; i < 16; ++i) sc[i] = 0.f;
; #pragma unroll
;             for (int ks = 0; ks < 4; ++ks) { const bf16x8 a = *(const LAS bf16x8*)(L + NL_KC + (32 * ct + r) * 144 + (16 * ks + 8 * h) * 2); sc = MFMA32(a, qu[ks], sc); }
; #pragma unroll
;             for (int i = 0; i < 16; ++i) { const int c = 32 * ct + (i & 3) + 8 * (i >> 2) + 4 * h; mx = fmaxf(mx, sc[i] + __int_as_float(((cmax - c) >> 31) & (int)0xF149F2CA)); }
;         }
	v_mfma_f32_32x32x16_bf16 v[2:17], v[20:23], v[62:65], v[2:17]
	v_cndmask_b32_e64 v20, 0, v234, s[0:1]
	v_cmp_gt_i32_e64 s[0:1], v18, v204
	s_nop 9
	v_add_f32_e32 v20, v2, v20
	v_cndmask_b32_e64 v2, v234, 0, s[0:1]
	v_add_f32_e32 v21, v3, v2
	s_mov_b32 s0, 0xe0ad78ec
	v_or_b32_e32 v3, 2, v204
	v_max3_f32 v2, v20, s0, v21
	v_cmp_lt_i32_e64 s[0:1], v18, v3
	s_nop 1
	v_cndmask_b32_e64 v3, 0, v234, s[0:1]
	v_add_f32_e32 v22, v4, v3
	v_or_b32_e32 v3, 3, v204
	v_cmp_lt_i32_e64 s[0:1], v18, v3
	s_nop 1
	v_cndmask_b32_e64 v3, 0, v234, s[0:1]
	v_add_f32_e32 v23, v5, v3
	v_or_b32_e32 v3, 8, v204
	v_cmp_lt_i32_e64 s[0:1], v18, v3
	v_max3_f32 v2, v2, v22, v23
	s_nop 0
	v_cndmask_b32_e64 v3, 0, v234, s[0:1]
	v_add_f32_e32 v24, v6, v3
	v_or_b32_e32 v3, 9, v204
	v_cmp_lt_i32_e64 s[0:1], v18, v3
	s_nop 1
	v_cndmask_b32_e64 v3, 0, v234, s[0:1]
	v_add_f32_e32 v25, v7, v3
	v_or_b32_e32 v3, 10, v204
	v_cmp_lt_i32_e64 s[0:1], v18, v3
	v_max3_f32 v2, v2, v24, v25
	s_nop 0
	v_cndmask_b32_e64 v3, 0, v234, s[0:1]
	v_add_f32_e32 v26, v8, v3
	v_or_b32_e32 v3, 11, v204
	v_cmp_lt_i32_e64 s[0:1], v18, v3
	s_nop 1
	v_cndmask_b32_e64 v3, 0, v234, s[0:1]
	v_add_f32_e32 v27, v9, v3
	v_or_b32_e32 v3, 16, v204
	v_cmp_lt_i32_e64 s[0:1], v18, v3
	v_max3_f32 v2, v2, v26, v27
	s_nop 0
	v_cndmask_b32_e64 v3, 0, v234, s[0:1]
	v_add_f32_e32 v28, v10, v3
	v_or_b32_e32 v3, 17, v204
	v_cmp_lt_i32_e64 s[0:1], v18, v3
	s_nop 1
	v_cndmask_b32_e64 v3, 0, v234, s[0:1]
	v_add_f32_e32 v29, v11, v3
	v_or_b32_e32 v3, 18, v204
	v_cmp_lt_i32_e64 s[0:1], v18, v3
	v_max3_f32 v2, v2, v28, v29
	s_nop 0
	v_cndmask_b32_e64 v3, 0, v234, s[0:1]
	v_add_f32_e32 v30, v12, v3
	v_or_b32_e32 v3, 19, v204
	v_cmp_lt_i32_e64 s[0:1], v18, v3
	s_nop 1
	v_cndmask_b32_e64 v3, 0, v234, s[0:1]
	v_add_f32_e32 v31, v13, v3
	v_or_b32_e32 v3, 24, v204
	v_cmp_lt_i32_e64 s[0:1], v18, v3
	v_max3_f32 v2, v2, v30, v31
	s_nop 0
	v_cndmask_b32_e64 v3, 0, v234, s[0:1]
	v_add_f32_e32 v32, v14, v3
	v_or_b32_e32 v3, 25, v204
	v_cmp_lt_i32_e64 s[0:1], v18, v3
	s_nop 1
	v_cndmask_b32_e64 v3, 0, v234, s[0:1]
	v_add_f32_e32 v33, v15, v3
	v_or_b32_e32 v3, 26, v204
	v_cmp_lt_i32_e64 s[0:1], v18, v3
	v_max3_f32 v2, v2, v32, v33
	s_nop 0
	v_cndmask_b32_e64 v3, 0, v234, s[0:1]
	v_add_f32_e32 v34, v16, v3
	v_or_b32_e32 v3, 27, v204
	v_cmp_lt_i32_e64 s[0:1], v18, v3
	s_nop 1
	v_cndmask_b32_e64 v3, 0, v234, s[0:1]
	v_add_f32_e32 v42, v17, v3
	v_max3_f32 v35, v2, v34, v42
	ds_read_b128 v[2:5], v100 offset:4608
	s_waitcnt lgkmcnt(0)
	v_mfma_f32_32x32x16_bf16 v[2:17], v[2:5], v[58:61], 0
	v_mfma_f32_32x32x16_bf16 v[2:17], v[36:39], v[54:57], v[2:17]
	ds_read_b128 v[36:39], v100 offset:4672
	s_waitcnt lgkmcnt(0)
	v_mfma_f32_32x32x16_bf16 v[2:17], v[36:39], v[50:53], v[2:17]
	ds_read_b128 v[36:39], v100 offset:4704
	s_waitcnt lgkmcnt(0)
	v_mfma_f32_32x32x16_bf16 v[2:17], v[36:39], v[62:65], v[2:17]
	v_or_b32_e32 v36, 32, v204
	v_cmp_lt_i32_e64 s[0:1], v18, v36
	s_nop 1
	v_cndmask_b32_e64 v82, 0, v234, s[0:1]
	v_cmp_gt_i32_e64 s[0:1], v18, v36
	ds_read_b128 v[36:39], v100 offset:9248
	s_nop 4
	v_add_f32_e32 v2, v2, v82
	v_cndmask_b32_e64 v79, v234, 0, s[0:1]
	v_add_f32_e32 v3, v3, v79
	v_max3_f32 v2, v35, v2, v3
	v_or_b32_e32 v3, 34, v204
	v_cmp_lt_i32_e64 s[0:1], v18, v3
	s_nop 1
	v_cndmask_b32_e64 v93, 0, v234, s[0:1]
	v_add_f32_e32 v3, v4, v93
	v_or_b32_e32 v4, 35, v204
	v_cmp_lt_i32_e64 s[0:1], v18, v4
	s_nop 1
	v_cndmask_b32_e64 v95, 0, v234, s[0:1]
	v_add_f32_e32 v4, v5, v95
	v_max3_f32 v2, v2, v3, v4
	v_or_b32_e32 v3, 40, v204
	v_cmp_lt_i32_e64 s[0:1], v18, v3
	v_or_b32_e32 v4, 41, v204
	s_nop 0
	v_cndmask_b32_e64 v86, 0, v234, s[0:1]
	v_cmp_lt_i32_e64 s[0:1], v18, v4
	v_add_f32_e32 v3, v6, v86
	s_nop 0
	v_cndmask_b32_e64 v90, 0, v234, s[0:1]
	v_add_f32_e32 v4, v7, v90
	v_max3_f32 v2, v2, v3, v4
	v_or_b32_e32 v3, 42, v204
	v_cmp_lt_i32_e64 s[0:1], v18, v3
	v_or_b32_e32 v4, 43, v204
	s_nop 0
	v_cndmask_b32_e64 v92, 0, v234, s[0:1]
	v_cmp_lt_i32_e64 s[0:1], v18, v4
	v_add_f32_e32 v3, v8, v92
	s_nop 0
	v_cndmask_b32_e64 v94, 0, v234, s[0:1]
	v_add_f32_e32 v4, v9, v94
	v_max3_f32 v2, v2, v3, v4
	v_or_b32_e32 v3, 48, v204
	v_cmp_lt_i32_e64 s[0:1], v18, v3
	v_or_b32_e32 v4, 49, v204
	s_nop 0
	v_cndmask_b32_e64 v150, 0, v234, s[0:1]
	v_cmp_lt_i32_e64 s[0:1], v18, v4
	v_add_f32_e32 v3, v10, v150
	s_nop 0
	v_cndmask_b32_e64 v149, 0, v234, s[0:1]
	v_add_f32_e32 v4, v11, v149
	v_max3_f32 v2, v2, v3, v4
	v_or_b32_e32 v3, 50, v204
	v_cmp_lt_i32_e64 s[0:1], v18, v3
	v_or_b32_e32 v4, 51, v204
	s_nop 0
	v_cndmask_b32_e64 v148, 0, v234, s[0:1]
	v_cmp_lt_i32_e64 s[0:1], v18, v4
	v_add_f32_e32 v3, v12, v148
	s_nop 0
	v_cndmask_b32_e64 v147, 0, v234, s[0:1]
	v_add_f32_e32 v4, v13, v147
	v_max3_f32 v2, v2, v3, v4
	v_or_b32_e32 v3, 56, v204
	v_cmp_lt_i32_e64 s[0:1], v18, v3
	v_or_b32_e32 v4, 57, v204
	s_nop 0
	v_cndmask_b32_e64 v88, 0, v234, s[0:1]
	v_cmp_lt_i32_e64 s[0:1], v18, v4
	v_add_f32_e32 v3, v14, v88
	s_nop 0
	v_cndmask_b32_e64 v89, 0, v234, s[0:1]
	v_add_f32_e32 v4, v15, v89
	v_max3_f32 v2, v2, v3, v4
	v_or_b32_e32 v3, 58, v204
	v_cmp_lt_i32_e64 s[0:1], v18, v3
	v_or_b32_e32 v4, 59, v204
	s_nop 0
	v_cndmask_b32_e64 v143, 0, v234, s[0:1]
	v_cmp_lt_i32_e64 s[0:1], v18, v4
	v_add_f32_e32 v3, v16, v143
	s_nop 0
	v_cndmask_b32_e64 v144, 0, v234, s[0:1]
	v_add_f32_e32 v4, v17, v144
	v_max3_f32 v35, v2, v3, v4
	ds_read_b128 v[2:5], v100 offset:9216
	s_waitcnt lgkmcnt(0)
	v_mfma_f32_32x32x16_bf16 v[2:17], v[2:5], v[58:61], 0
	v_mfma_f32_32x32x16_bf16 v[2:17], v[36:39], v[54:57], v[2:17]
	ds_read_b128 v[36:39], v100 offset:9280
	s_waitcnt lgkmcnt(0)
	v_mfma_f32_32x32x16_bf16 v[2:17], v[36:39], v[50:53], v[2:17]
	ds_read_b128 v[36:39], v100 offset:9312
	s_waitcnt lgkmcnt(0)
; #define LAS __attribute__((address_space(3)))
; #define MFMA32(a, b, c) __builtin_amdgcn_mfma_f32_32x32x16_bf16((a), (b), (c), 0, 0, 0)
; __device__ __forceinline__ void nsa_unit(const Frame& F, int plane, int qt) {
;     ...
;         for (int ct = 0; ct < 4; ++ct) {
;             f32x16 sc;
; #pragma unroll
;             for (int i = 0; i < 16; ++i) sc[i] = 0.f;
; #pragma unroll
;             for (int ks = 0; ks < 4; ++ks) { const bf16x8 a = *(const LAS bf16x8*)(L + NL_KC + (32 * ct + r) * 144 + (16 * ks + 8 * h) * 2); sc = MFMA32(a, qu[ks], sc); }
; #pragma unroll
;             for (int i = 0; i < 16; ++i) { const int c = 32 * ct + (i & 3) + 8 * (i >> 2) + 4 * h; mx = fmaxf(mx, sc[i] + __int_as_float(((cmax - c) >> 31) & (int)0xF149F2CA)); }
;         }
;         mx = fmaxf(mx, __shfl_xor(mx, 32));
	v_mfma_f32_32x32x16_bf16 v[2:17], v[36:39], v[62:65], v[2:17]
	v_or_b32_e32 v36, 64, v204
	v_cmp_lt_i32_e64 s[0:1], v18, v36
	s_nop 1
	v_cndmask_b32_e64 v105, 0, v234, s[0:1]
	v_cmp_gt_i32_e64 s[0:1], v18, v36
	ds_read_b128 v[36:39], v100 offset:13856
	s_nop 4
	v_add_f32_e32 v2, v2, v105
	v_cndmask_b32_e64 v104, v234, 0, s[0:1]
	v_add_f32_e32 v3, v3, v104
	v_max3_f32 v2, v35, v2, v3
	v_or_b32_e32 v3, 0x42, v204
	v_cmp_lt_i32_e64 s[0:1], v18, v3
	s_nop 1
	v_cndmask_b32_e64 v106, 0, v234, s[0:1]
	v_add_f32_e32 v3, v4, v106
	v_or_b32_e32 v4, 0x43, v204
	v_cmp_lt_i32_e64 s[0:1], v18, v4
	s_nop 1
	v_cndmask_b32_e64 v107, 0, v234, s[0:1]
	v_add_f32_e32 v4, v5, v107
	v_max3_f32 v2, v2, v3, v4
	v_or_b32_e32 v3, 0x48, v204
	v_cmp_lt_i32_e64 s[0:1], v18, v3
	v_or_b32_e32 v4, 0x49, v204
	s_nop 0
	v_cndmask_b32_e64 v108, 0, v234, s[0:1]
	v_cmp_lt_i32_e64 s[0:1], v18, v4
	v_add_f32_e32 v3, v6, v108
	s_nop 0
	v_cndmask_b32_e64 v109, 0, v234, s[0:1]
	v_add_f32_e32 v4, v7, v109
	v_max3_f32 v2, v2, v3, v4
	v_or_b32_e32 v3, 0x4a, v204
	v_cmp_lt_i32_e64 s[0:1], v18, v3
	v_or_b32_e32 v4, 0x4b, v204
	s_nop 0
	v_cndmask_b32_e64 v110, 0, v234, s[0:1]
	v_cmp_lt_i32_e64 s[0:1], v18, v4
	v_add_f32_e32 v3, v8, v110
	s_nop 0
	v_cndmask_b32_e64 v111, 0, v234, s[0:1]
	v_add_f32_e32 v4, v9, v111
	v_max3_f32 v2, v2, v3, v4
	v_or_b32_e32 v3, 0x50, v204
	v_cmp_lt_i32_e64 s[0:1], v18, v3
	v_or_b32_e32 v4, 0x51, v204
	s_nop 0
	v_cndmask_b32_e64 v112, 0, v234, s[0:1]
	v_cmp_lt_i32_e64 s[0:1], v18, v4
	v_add_f32_e32 v3, v10, v112
	s_nop 0
	v_cndmask_b32_e64 v113, 0, v234, s[0:1]
	v_add_f32_e32 v4, v11, v113
	v_max3_f32 v2, v2, v3, v4
	v_or_b32_e32 v3, 0x52, v204
	v_cmp_lt_i32_e64 s[0:1], v18, v3
	v_or_b32_e32 v4, 0x53, v204
	s_nop 0
	v_cndmask_b32_e64 v115, 0, v234, s[0:1]
	v_cmp_lt_i32_e64 s[0:1], v18, v4
	v_add_f32_e32 v3, v12, v115
	s_nop 0
	v_cndmask_b32_e64 v116, 0, v234, s[0:1]
	v_add_f32_e32 v4, v13, v116
	v_max3_f32 v2, v2, v3, v4
	v_or_b32_e32 v3, 0x58, v204
	v_cmp_lt_i32_e64 s[0:1], v18, v3
	v_or_b32_e32 v4, 0x59, v204
	s_nop 0
	v_cndmask_b32_e64 v117, 0, v234, s[0:1]
	v_cmp_lt_i32_e64 s[0:1], v18, v4
	v_add_f32_e32 v3, v14, v117
	s_nop 0
	v_cndmask_b32_e64 v101, 0, v234, s[0:1]
	v_add_f32_e32 v4, v15, v101
	v_max3_f32 v2, v2, v3, v4
	v_or_b32_e32 v3, 0x5a, v204
	v_cmp_lt_i32_e64 s[0:1], v18, v3
	v_or_b32_e32 v4, 0x5b, v204
	s_nop 0
	v_cndmask_b32_e64 v102, 0, v234, s[0:1]
	v_cmp_lt_i32_e64 s[0:1], v18, v4
	v_add_f32_e32 v3, v16, v102
	s_nop 0
	v_cndmask_b32_e64 v103, 0, v234, s[0:1]
	v_add_f32_e32 v4, v17, v103
	v_max3_f32 v35, v2, v3, v4
	ds_read_b128 v[2:5], v100 offset:13824
	s_waitcnt lgkmcnt(0)
	v_mfma_f32_32x32x16_bf16 v[2:17], v[2:5], v[58:61], 0
	v_mfma_f32_32x32x16_bf16 v[2:17], v[36:39], v[54:57], v[2:17]
	ds_read_b128 v[36:39], v100 offset:13888
	s_waitcnt lgkmcnt(0)
	v_mfma_f32_32x32x16_bf16 v[2:17], v[36:39], v[50:53], v[2:17]
	ds_read_b128 v[36:39], v100 offset:13920
	s_waitcnt lgkmcnt(0)
	v_mfma_f32_32x32x16_bf16 v[2:17], v[36:39], v[62:65], v[2:17]
	v_or_b32_e32 v36, 0x60, v204
	v_cmp_lt_i32_e64 s[0:1], v18, v36
	s_nop 1
	v_cndmask_b32_e64 v125, 0, v234, s[0:1]
	v_cmp_gt_i32_e64 s[0:1], v18, v36
	s_nop 5
	v_add_f32_e32 v2, v2, v125
	v_cndmask_b32_e64 v121, v234, 0, s[0:1]
	v_add_f32_e32 v3, v3, v121
	v_max3_f32 v2, v35, v2, v3
	v_or_b32_e32 v3, 0x62, v204
	v_cmp_lt_i32_e64 s[0:1], v18, v3
	s_nop 1
	v_cndmask_b32_e64 v129, 0, v234, s[0:1]
	v_add_f32_e32 v3, v4, v129
	v_or_b32_e32 v4, 0x63, v204
	v_cmp_lt_i32_e64 s[0:1], v18, v4
	s_nop 1
	v_cndmask_b32_e64 v132, 0, v234, s[0:1]
	v_add_f32_e32 v4, v5, v132
	v_max3_f32 v2, v2, v3, v4
	v_or_b32_e32 v3, 0x68, v204
	v_cmp_lt_i32_e64 s[0:1], v18, v3
	v_or_b32_e32 v4, 0x69, v204
	s_nop 0
	v_cndmask_b32_e64 v133, 0, v234, s[0:1]
	v_cmp_lt_i32_e64 s[0:1], v18, v4
	v_add_f32_e32 v3, v6, v133
	s_nop 0
	v_cndmask_b32_e64 v134, 0, v234, s[0:1]
	v_add_f32_e32 v4, v7, v134
	v_max3_f32 v2, v2, v3, v4
	v_or_b32_e32 v3, 0x6a, v204
	v_cmp_lt_i32_e64 s[0:1], v18, v3
	v_or_b32_e32 v4, 0x6b, v204
	s_nop 0
	v_cndmask_b32_e64 v135, 0, v234, s[0:1]
	v_cmp_lt_i32_e64 s[0:1], v18, v4
	v_add_f32_e32 v3, v8, v135
	s_nop 0
	v_cndmask_b32_e64 v136, 0, v234, s[0:1]
	v_add_f32_e32 v4, v9, v136
	v_max3_f32 v2, v2, v3, v4
	v_or_b32_e32 v3, 0x70, v204
	v_cmp_lt_i32_e64 s[0:1], v18, v3
	v_or_b32_e32 v4, 0x71, v204
	s_nop 0
	v_cndmask_b32_e64 v138, 0, v234, s[0:1]
	v_cmp_lt_i32_e64 s[0:1], v18, v4
	v_add_f32_e32 v3, v10, v138
	s_nop 0
	v_cndmask_b32_e64 v139, 0, v234, s[0:1]
	v_add_f32_e32 v4, v11, v139
	v_max3_f32 v2, v2, v3, v4
	v_or_b32_e32 v3, 0x72, v204
	v_cmp_lt_i32_e64 s[0:1], v18, v3
	v_or_b32_e32 v4, 0x73, v204
	s_nop 0
	v_cndmask_b32_e64 v140, 0, v234, s[0:1]
	v_cmp_lt_i32_e64 s[0:1], v18, v4
	v_add_f32_e32 v3, v12, v140
	s_nop 0
	v_cndmask_b32_e64 v141, 0, v234, s[0:1]
	v_add_f32_e32 v4, v13, v141
	v_max3_f32 v2, v2, v3, v4
	v_or_b32_e32 v3, 0x78, v204
	v_cmp_lt_i32_e64 s[0:1], v18, v3
	v_or_b32_e32 v4, 0x79, v204
	s_nop 0
	v_cndmask_b32_e64 v142, 0, v234, s[0:1]
	v_cmp_lt_i32_e64 s[0:1], v18, v4
	v_add_f32_e32 v3, v14, v142
	v_sub_u32_e32 v14, v19, v206
	v_cndmask_b32_e64 v118, 0, v234, s[0:1]
	v_add_f32_e32 v4, v15, v118
	v_max3_f32 v2, v2, v3, v4
	v_or_b32_e32 v3, 0x7a, v204
	v_cmp_lt_i32_e64 s[0:1], v18, v3
	v_or_b32_e32 v4, 0x7b, v204
	s_nop 0
	v_cndmask_b32_e64 v119, 0, v234, s[0:1]
	v_cmp_lt_i32_e64 s[0:1], v18, v4
	v_add_f32_e32 v3, v16, v119
	s_nop 0
	v_cndmask_b32_e64 v120, 0, v234, s[0:1]
	v_add_f32_e32 v4, v17, v120
	v_max3_f32 v2, v2, v3, v4
	ds_bpermute_b32 v3, v205, v2
	v_cmp_eq_u32_e64 s[0:1], s8, v1
	s_or_b64 s[0:1], vcc, s[0:1]
	s_waitcnt lgkmcnt(0)
; #define LAS __attribute__((address_space(3)))
; #define MFMA32(a, b, c) __builtin_amdgcn_mfma_f32_32x32x16_bf16((a), (b), (c), 0, 0, 0)
; __device__ __forceinline__ void nsa_unit(const Frame& F, int plane, int qt) {
;     ...
;         for (int ct = 0; ct < 4; ++ct) {
;             f32x16 sc;
; #pragma unroll
;             for (int i = 0; i < 16; ++i) sc[i] = 0.f;
; #pragma unroll
;             for (int ks = 0; ks < 4; ++ks) { const bf16x8 a = *(const LAS bf16x8*)(L + NL_KC + (32 * ct + r) * 144 + (16 * ks + 8 * h) * 2); sc = MFMA32(a, qu[ks], sc); }
; #pragma unroll
;             for (int i = 0; i < 16; ++i) { const int c = 32 * ct + (i & 3) + 8 * (i >> 2) + 4 * h; const float e = __builtin_amdgcn_exp2f(sc[i] + __int_as_float(((cmax - c) >> 31) & (int)0xF149F2CA) - mx); sc[i] = e; ls += e; }
; #pragma unroll
;             for (int q = 0; q < 4; ++q) { const float ok = __shfl_xor(sc[4 * q + 3], 32);
;                 imp[4 * ct + q] = ((sc[4 * q] + sc[4 * q + 1]) + (sc[4 * q + 2] + sc[4 * q + 3])) + (h ? ok : prev); prev = ok; }
; #pragma unroll
;             for (int s2 = 0; s2 < 2; ++s2) { const bf16x8 pf = pack_step(sc, s2);
; #pragma unroll
;                 for (int dt = 0; dt < 2; ++dt) { const LAS unsigned char* vp = L + NL_VC + (32 * dt + r) * 272 + (32 * ct + 16 * s2 + 4 * h) * 2;
;                     const s16x4 lo = *(const LAS s16x4*)vp, hi = *(const LAS s16x4*)(vp + 16);
;                     const bf16x8 vf = __builtin_shufflevector(lo, hi, 0, 1, 2, 3, 4, 5, 6, 7);
;                     outacc[dt] = MFMA32(vf, pf, outacc[dt]); } }
;             __builtin_amdgcn_sched_barrier(0);
	v_max_f32_e32 v3, v3, v3
	v_max_f32_e32 v137, v2, v3
	v_sub_f32_e32 v2, v20, v137
	v_exp_f32_e32 v3, v2
	v_sub_f32_e32 v2, v21, v137
	v_sub_f32_e32 v10, v28, v137
	v_exp_f32_e32 v5, v2
	v_sub_f32_e32 v2, v22, v137
	v_exp_f32_e32 v37, v10
	v_sub_f32_e32 v10, v29, v137
	v_exp_f32_e32 v7, v2
	v_sub_f32_e32 v2, v23, v137
	v_exp_f32_e32 v39, v10
	v_sub_f32_e32 v10, v30, v137
	v_exp_f32_e32 v9, v2
	v_sub_f32_e32 v2, v24, v137
	v_sub_f32_e32 v4, v25, v137
	v_sub_f32_e32 v6, v26, v137
	v_sub_f32_e32 v8, v27, v137
	v_exp_f32_e32 v41, v10
	v_sub_f32_e32 v10, v31, v137
	v_exp_f32_e32 v2, v2
	v_exp_f32_e32 v4, v4
	v_exp_f32_e32 v6, v6
	v_exp_f32_e32 v8, v8
	v_exp_f32_e32 v35, v10
	v_sub_f32_e32 v10, v32, v137
	v_exp_f32_e32 v36, v10
	v_sub_f32_e32 v10, v33, v137
	v_exp_f32_e32 v38, v10
	v_sub_f32_e32 v10, v34, v137
	v_exp_f32_e32 v40, v10
	v_sub_f32_e32 v10, v42, v137
	v_exp_f32_e32 v34, v10
	v_pk_add_f32 v[10:11], v[2:3], v[4:5]
	v_pk_add_f32 v[12:13], v[6:7], v[8:9]
	ds_bpermute_b32 v45, v205, v9
	v_pk_add_f32 v[42:43], v[10:11], v[12:13]
	v_add_f32_e32 v10, 0, v3
	ds_bpermute_b32 v151, v205, v8
	v_add_f32_e32 v10, v5, v10
	v_add_f32_e32 v10, v7, v10
	v_add_f32_e32 v10, v9, v10
	v_add_f32_e32 v10, v2, v10
	v_mad_u32_u24 v22, v83, s11, v14
	v_add_f32_e32 v10, v4, v10
	v_add_u32_e32 v145, 0x4800, v22
	v_add_f32_e32 v10, v6, v10
	v_cvt_pk_bf16_f32 v18, v3, v5
	v_cvt_pk_bf16_f32 v19, v7, v9
	v_cvt_pk_bf16_f32 v20, v2, v4
	v_cvt_pk_bf16_f32 v21, v6, v8
	s_nop 1
	ds_read2_b64 v[2:5], v145 offset1:2
	s_waitcnt lgkmcnt(1)
	v_cndmask_b32_e32 v44, v151, v45, vcc
	v_cndmask_b32_e64 v45, v45, 0, vcc
	v_add_f32_e32 v46, v8, v10
	v_pk_add_f32 v[80:81], v[44:45], v[42:43]
	v_pk_add_f32 v[42:43], v[36:37], v[38:39]
	v_pk_add_f32 v[44:45], v[40:41], v[34:35]
	v_add_u32_e32 v146, 0x6800, v22
	v_pk_add_f32 v[84:85], v[42:43], v[44:45]
	v_add_f32_e32 v42, v37, v46
	v_add_f32_e32 v42, v39, v42
	v_add_f32_e32 v42, v41, v42
	v_add_f32_e32 v42, v35, v42
	v_add_f32_e32 v42, v36, v42
	v_add_f32_e32 v42, v38, v42
	ds_read2_b64 v[22:25], v146 offset0:64 offset1:66
	v_add_f32_e32 v46, v40, v42
	v_cvt_pk_bf16_f32 v42, v37, v39
	v_cvt_pk_bf16_f32 v43, v41, v35
	v_cvt_pk_bf16_f32 v44, v36, v38
	v_cvt_pk_bf16_f32 v45, v40, v34
	s_nop 1
	ds_read2_b64 v[36:39], v145 offset0:4 offset1:6
	s_waitcnt lgkmcnt(2)
	v_mfma_f32_32x32x16_bf16 v[2:17], v[2:5], v[18:21], 0
	ds_bpermute_b32 v153, v205, v35
	ds_bpermute_b32 v152, v205, v34
	v_add_f32_e32 v158, v34, v46
	s_waitcnt lgkmcnt(2)
	v_mfma_f32_32x32x16_bf16 v[2:17], v[36:39], v[42:45], v[2:17]
	ds_read2_b64 v[36:39], v146 offset0:68 offset1:70
	v_mfma_f32_32x32x16_bf16 v[18:33], v[22:25], v[18:21], 0
	s_waitcnt lgkmcnt(0)
	v_mfma_f32_32x32x16_bf16 v[18:33], v[36:39], v[42:45], v[18:33]
	ds_read_b128 v[34:37], v100 offset:4608
	ds_read_b128 v[154:157], v100 offset:4640
	s_waitcnt lgkmcnt(1)
	v_mfma_f32_32x32x16_bf16 v[34:49], v[34:37], v[58:61], 0
	s_waitcnt lgkmcnt(0)
	v_mfma_f32_32x32x16_bf16 v[34:49], v[154:157], v[54:57], v[34:49]
	ds_read_b128 v[154:157], v100 offset:4672
	s_waitcnt lgkmcnt(0)
	v_mfma_f32_32x32x16_bf16 v[34:49], v[154:157], v[50:53], v[34:49]
	ds_read_b128 v[154:157], v100 offset:4704
	s_waitcnt lgkmcnt(0)
	v_mfma_f32_32x32x16_bf16 v[34:49], v[154:157], v[62:65], v[34:49]
	s_nop 11
	v_add_f32_e32 v34, v34, v82
	v_sub_f32_e32 v34, v34, v137
	v_exp_f32_e32 v87, v34
	v_add_f32_e32 v34, v35, v79
	v_sub_f32_e32 v34, v34, v137
	v_exp_f32_e32 v91, v34
	v_add_f32_e32 v34, v36, v93
	v_sub_f32_e32 v34, v34, v137
	v_exp_f32_e32 v93, v34
	v_add_f32_e32 v34, v37, v95
	v_sub_f32_e32 v34, v34, v137
	v_exp_f32_e32 v95, v34
	v_add_f32_e32 v34, v38, v86
	v_sub_f32_e32 v34, v34, v137
	v_exp_f32_e32 v86, v34
	v_add_f32_e32 v34, v39, v90
	v_sub_f32_e32 v34, v34, v137
	v_exp_f32_e32 v90, v34
	v_add_f32_e32 v34, v40, v92
	v_sub_f32_e32 v34, v34, v137
	v_exp_f32_e32 v92, v34
	v_add_f32_e32 v34, v41, v94
	v_sub_f32_e32 v34, v34, v137
	v_exp_f32_e32 v94, v34
	v_add_f32_e32 v34, v42, v150
	v_sub_f32_e32 v34, v34, v137
	v_exp_f32_e32 v35, v34
	v_add_f32_e32 v34, v43, v149
	v_sub_f32_e32 v34, v34, v137
	v_exp_f32_e32 v37, v34
	v_add_f32_e32 v34, v44, v148
	v_sub_f32_e32 v34, v34, v137
	v_exp_f32_e32 v39, v34
	v_add_f32_e32 v34, v45, v147
	v_sub_f32_e32 v34, v34, v137
	v_exp_f32_e32 v41, v34
	v_add_f32_e32 v34, v46, v88
	v_add_f32_e32 v36, v47, v89
	v_add_f32_e32 v38, v48, v143
	v_add_f32_e32 v40, v49, v144
	v_sub_f32_e32 v34, v34, v137
	v_sub_f32_e32 v36, v36, v137
	v_sub_f32_e32 v38, v38, v137
	v_sub_f32_e32 v40, v40, v137
	v_exp_f32_e32 v34, v34
	v_exp_f32_e32 v36, v36
	v_exp_f32_e32 v38, v38
	v_exp_f32_e32 v40, v40
	ds_bpermute_b32 v143, v205, v95
	v_pk_add_f32 v[42:43], v[34:35], v[36:37]
	ds_bpermute_b32 v144, v205, v94
	v_pk_add_f32 v[44:45], v[38:39], v[40:41]
	v_or_b32_e32 v79, 4, v1
	v_pk_add_f32 v[88:89], v[42:43], v[44:45]
	v_cndmask_b32_e32 v43, v153, v151, vcc
	v_cndmask_b32_e32 v42, v152, v153, vcc
	v_pk_add_f32 v[84:85], v[84:85], v[42:43]
	v_pk_add_f32 v[42:43], v[86:87], v[90:91]
	v_pk_add_f32 v[44:45], v[92:93], v[94:95]
	v_or_b32_e32 v82, 6, v1
	v_pk_add_f32 v[148:149], v[42:43], v[44:45]
	v_add_f32_e32 v42, v87, v158
	v_add_f32_e32 v42, v91, v42
	v_add_f32_e32 v42, v93, v42
	v_add_f32_e32 v42, v95, v42
	v_add_f32_e32 v42, v86, v42
	v_add_f32_e32 v42, v90, v42
	v_add_f32_e32 v42, v92, v42
	v_add_f32_e32 v147, v94, v42
	v_cvt_pk_bf16_f32 v42, v87, v91
	v_cvt_pk_bf16_f32 v43, v93, v95
	v_cvt_pk_bf16_f32 v44, v86, v90
	v_cvt_pk_bf16_f32 v45, v92, v94
	s_nop 1
	ds_read2_b64 v[46:49], v145 offset0:8 offset1:10
	s_waitcnt lgkmcnt(0)
	v_mfma_f32_32x32x16_bf16 v[2:17], v[46:49], v[42:45], v[2:17]
	ds_read2_b64 v[46:49], v146 offset0:72 offset1:74
	ds_bpermute_b32 v150, v205, v41
	s_waitcnt lgkmcnt(1)
; #define LAS __attribute__((address_space(3)))
; #define MFMA32(a, b, c) __builtin_amdgcn_mfma_f32_32x32x16_bf16((a), (b), (c), 0, 0, 0)
; __device__ __forceinline__ void nsa_unit(const Frame& F, int plane, int qt) {
;     ...
;         for (int ct = 0; ct < 4; ++ct) {
;             f32x16 sc;
; #pragma unroll
;             for (int i = 0; i < 16; ++i) sc[i] = 0.f;
; #pragma unroll
;             for (int ks = 0; ks < 4; ++ks) { const bf16x8 a = *(const LAS bf16x8*)(L + NL_KC + (32 * ct + r) * 144 + (16 * ks + 8 * h) * 2); sc = MFMA32(a, qu[ks], sc); }
; #pragma unroll
;             for (int i = 0; i < 16; ++i) { const int c = 32 * ct + (i & 3) + 8 * (i >> 2) + 4 * h; const float e = __builtin_amdgcn_exp2f(sc[i] + __int_as_float(((cmax - c) >> 31) & (int)0xF149F2CA) - mx); sc[i] = e; ls += e; }
; #pragma unroll
;             for (int q = 0; q < 4; ++q) { const float ok = __shfl_xor(sc[4 * q + 3], 32);
;                 imp[4 * ct + q] = ((sc[4 * q] + sc[4 * q + 1]) + (sc[4 * q + 2] + sc[4 * q + 3])) + (h ? ok : prev); prev = ok; }
; #pragma unroll
;             for (int s2 = 0; s2 < 2; ++s2) { const bf16x8 pf = pack_step(sc, s2);
; #pragma unroll
;                 for (int dt = 0; dt < 2; ++dt) { const LAS unsigned char* vp = L + NL_VC + (32 * dt + r) * 272 + (32 * ct + 16 * s2 + 4 * h) * 2;
;                     const s16x4 lo = *(const LAS s16x4*)vp, hi = *(const LAS s16x4*)(vp + 16);
;                     const bf16x8 vf = __builtin_shufflevector(lo, hi, 0, 1, 2, 3, 4, 5, 6, 7);
;                     outacc[dt] = MFMA32(vf, pf, outacc[dt]); } }
;             __builtin_amdgcn_sched_barrier(0);
	v_mfma_f32_32x32x16_bf16 v[18:33], v[46:49], v[42:45], v[18:33]
	v_cndmask_b32_e32 v43, v143, v152, vcc
	v_cndmask_b32_e32 v42, v144, v143, vcc
	v_add_f32_e64 v86, v148, v42
	v_add_f32_e64 v87, v149, v43
	v_add_f32_e32 v42, v35, v147
	v_add_f32_e32 v42, v37, v42
	v_add_f32_e32 v42, v39, v42
	v_add_f32_e32 v42, v41, v42
	v_add_f32_e32 v42, v34, v42
	v_add_f32_e32 v42, v36, v42
	v_add_f32_e32 v46, v38, v42
	v_cvt_pk_bf16_f32 v42, v35, v37
	v_cvt_pk_bf16_f32 v43, v39, v41
	v_cvt_pk_bf16_f32 v44, v34, v36
	v_cvt_pk_bf16_f32 v45, v38, v40
	s_nop 1
	ds_read2_b64 v[34:37], v145 offset0:12 offset1:14
	s_waitcnt lgkmcnt(0)
	v_mfma_f32_32x32x16_bf16 v[2:17], v[34:37], v[42:45], v[2:17]
	ds_read2_b64 v[34:37], v146 offset0:76 offset1:78
	ds_bpermute_b32 v143, v205, v40
	v_add_f32_e32 v147, v40, v46
	s_waitcnt lgkmcnt(1)
	v_mfma_f32_32x32x16_bf16 v[18:33], v[34:37], v[42:45], v[18:33]
	ds_read_b128 v[34:37], v100 offset:9216
	ds_read_b128 v[90:93], v100 offset:9248
	s_waitcnt lgkmcnt(1)
	v_mfma_f32_32x32x16_bf16 v[34:49], v[34:37], v[58:61], 0
	s_waitcnt lgkmcnt(0)
	v_mfma_f32_32x32x16_bf16 v[34:49], v[90:93], v[54:57], v[34:49]
	ds_read_b128 v[90:93], v100 offset:9280
	s_waitcnt lgkmcnt(0)
	v_mfma_f32_32x32x16_bf16 v[34:49], v[90:93], v[50:53], v[34:49]
	ds_read_b128 v[90:93], v100 offset:9312
	s_waitcnt lgkmcnt(0)
	v_mfma_f32_32x32x16_bf16 v[34:49], v[90:93], v[62:65], v[34:49]
	s_nop 11
	v_add_f32_e32 v34, v34, v105
	v_sub_f32_e32 v34, v34, v137
	v_exp_f32_e32 v91, v34
	v_add_f32_e32 v34, v47, v101
	v_sub_f32_e32 v34, v34, v137
	v_add_f32_e32 v40, v40, v110
	v_exp_f32_e32 v110, v34
	v_add_f32_e32 v34, v48, v102
	v_sub_f32_e32 v34, v34, v137
	v_add_f32_e32 v42, v42, v112
	v_add_f32_e32 v43, v43, v113
	v_add_f32_e32 v44, v44, v115
	v_add_f32_e32 v45, v45, v116
	v_add_f32_e32 v46, v46, v117
	v_exp_f32_e32 v112, v34
	v_add_f32_e32 v34, v49, v103
	v_sub_f32_e32 v42, v42, v137
	v_sub_f32_e32 v43, v43, v137
	v_sub_f32_e32 v44, v44, v137
	v_sub_f32_e32 v45, v45, v137
	v_sub_f32_e32 v46, v46, v137
	v_sub_f32_e32 v34, v34, v137
	v_add_f32_e32 v38, v38, v108
	v_add_f32_e32 v39, v39, v109
	v_add_f32_e32 v41, v41, v111
	v_exp_f32_e32 v109, v42
	v_exp_f32_e32 v111, v43
	v_exp_f32_e32 v113, v44
	v_exp_f32_e32 v117, v45
	v_exp_f32_e32 v108, v46
	v_exp_f32_e32 v116, v34
	v_add_f32_e32 v35, v35, v104
	v_add_f32_e32 v36, v36, v106
	v_add_f32_e32 v37, v37, v107
	v_sub_f32_e32 v35, v35, v137
	v_sub_f32_e32 v36, v36, v137
	v_sub_f32_e32 v37, v37, v137
	v_sub_f32_e32 v38, v38, v137
	v_sub_f32_e32 v39, v39, v137
	v_sub_f32_e32 v40, v40, v137
	v_sub_f32_e32 v34, v41, v137
	v_exp_f32_e32 v95, v35
	v_exp_f32_e32 v105, v36
	v_exp_f32_e32 v107, v37
	v_exp_f32_e32 v90, v38
	v_exp_f32_e32 v94, v39
	v_exp_f32_e32 v104, v40
	v_exp_f32_e32 v106, v34
	v_pk_add_f32 v[34:35], v[108:109], v[110:111]
	v_pk_add_f32 v[36:37], v[112:113], v[116:117]
	v_cndmask_b32_e32 v43, v150, v144, vcc
	v_pk_add_f32 v[92:93], v[34:35], v[36:37]
	v_cvt_pk_bf16_f32 v34, v91, v95
	v_cvt_pk_bf16_f32 v35, v105, v107
	v_cvt_pk_bf16_f32 v36, v90, v94
	v_cvt_pk_bf16_f32 v37, v104, v106
	s_nop 1
	ds_read2_b64 v[38:41], v145 offset0:16 offset1:18
	v_cndmask_b32_e32 v42, v143, v150, vcc
	v_pk_add_f32 v[88:89], v[88:89], v[42:43]
	v_pk_add_f32 v[42:43], v[90:91], v[94:95]
	v_pk_add_f32 v[44:45], v[104:105], v[106:107]
	ds_bpermute_b32 v101, v205, v107
	v_pk_add_f32 v[102:103], v[42:43], v[44:45]
	v_add_f32_e32 v42, v91, v147
	v_add_f32_e32 v46, v95, v42
	ds_read2_b64 v[42:45], v146 offset0:80 offset1:82
	ds_bpermute_b32 v115, v205, v106
	s_waitcnt lgkmcnt(3)
	v_mfma_f32_32x32x16_bf16 v[2:17], v[38:41], v[34:37], v[2:17]
	v_add_f32_e32 v38, v105, v46
	v_add_f32_e32 v38, v107, v38
	v_add_f32_e32 v38, v90, v38
	v_add_f32_e32 v38, v94, v38
	v_add_f32_e32 v90, v104, v38
	v_cvt_pk_bf16_f32 v38, v109, v111
	v_cvt_pk_bf16_f32 v39, v113, v117
	v_cvt_pk_bf16_f32 v40, v108, v110
	v_cvt_pk_bf16_f32 v41, v112, v116
	s_nop 1
	ds_read2_b64 v[46:49], v145 offset0:20 offset1:22
	s_waitcnt lgkmcnt(2)
	v_mfma_f32_32x32x16_bf16 v[18:33], v[42:45], v[34:37], v[18:33]
	v_cndmask_b32_e32 v35, v101, v143, vcc
	s_waitcnt lgkmcnt(1)
	v_cndmask_b32_e32 v34, v115, v101, vcc
	v_add_f32_e32 v42, v106, v90
	v_add_f32_e64 v90, v102, v34
	v_add_f32_e64 v91, v103, v35
	ds_read2_b64 v[34:37], v146 offset0:84 offset1:86
	v_add_f32_e32 v42, v109, v42
	v_add_f32_e32 v42, v111, v42
	s_waitcnt lgkmcnt(1)
	v_mfma_f32_32x32x16_bf16 v[2:17], v[46:49], v[38:41], v[2:17]
	v_add_f32_e32 v42, v113, v42
	v_add_f32_e32 v42, v117, v42
	v_add_f32_e32 v42, v108, v42
	v_add_f32_e32 v42, v110, v42
	v_add_f32_e32 v42, v112, v42
	ds_bpermute_b32 v94, v205, v117
	ds_bpermute_b32 v95, v205, v116
	s_waitcnt lgkmcnt(2)
	v_mfma_f32_32x32x16_bf16 v[18:33], v[34:37], v[38:41], v[18:33]
	v_add_f32_e32 v101, v116, v42
	ds_read_b128 v[34:37], v100 offset:13824
	s_waitcnt lgkmcnt(0)
	v_mfma_f32_32x32x16_bf16 v[34:49], v[34:37], v[58:61], 0
	ds_read_b128 v[58:61], v100 offset:13856
	s_waitcnt lgkmcnt(0)
	v_mfma_f32_32x32x16_bf16 v[34:49], v[58:61], v[54:57], v[34:49]
	ds_read_b128 v[54:57], v100 offset:13888
	s_waitcnt lgkmcnt(0)
	v_mfma_f32_32x32x16_bf16 v[34:49], v[54:57], v[50:53], v[34:49]
	ds_read_b128 v[50:53], v100 offset:13920
	s_waitcnt lgkmcnt(0)
; #define LAS __attribute__((address_space(3)))
; #define MFMA32(a, b, c) __builtin_amdgcn_mfma_f32_32x32x16_bf16((a), (b), (c), 0, 0, 0)
; __device__ __forceinline__ void nsa_unit(const Frame& F, int plane, int qt) {
;     ...
;             for (int q = 0; q < 4; ++q) { const float ok = __shfl_xor(sc[4 * q + 3], 32);
;                 imp[4 * ct + q] = ((sc[4 * q] + sc[4 * q + 1]) + (sc[4 * q + 2] + sc[4 * q + 3])) + (h ? ok : prev); prev = ok; }
; #pragma unroll
;             for (int s2 = 0; s2 < 2; ++s2) { const bf16x8 pf = pack_step(sc, s2);
; #pragma unroll
;                 for (int dt = 0; dt < 2; ++dt) { const LAS unsigned char* vp = L + NL_VC + (32 * dt + r) * 272 + (32 * ct + 16 * s2 + 4 * h) * 2;
;                     const s16x4 lo = *(const LAS s16x4*)vp, hi = *(const LAS s16x4*)(vp + 16);
;                     const bf16x8 vf = __builtin_shufflevector(lo, hi, 0, 1, 2, 3, 4, 5, 6, 7);
;                     outacc[dt] = MFMA32(vf, pf, outacc[dt]); } }
;             __builtin_amdgcn_sched_barrier(0);
;         }
;         ls += __shfl_xor(ls, 32);
;         const float inv = ls > 0.f ? 1.f / ls : 0.f;
; #pragma unroll
;         for (int k = 0; k < 16; ++k) imp[k] *= inv;
;         { LAS float* ob = (LAS float*)(L + NL_OUT + w * 8192) + lane; const float og = inv * gate_c;
; #pragma unroll
;           for (int i = 0; i < 16; ++i) { ob[i * 64] = outacc[0][i] * og; ob[(16 + i) * 64] = outacc[1][i] * og; } }
; #pragma unroll
;         for (int k = 0; k < 16; ++k) { imp[k] += __shfl_xor(imp[k], 1); imp[k] += __shfl_xor(imp[k], 2);
	v_mfma_f32_32x32x16_bf16 v[34:49], v[50:53], v[62:65], v[34:49]
	s_nop 11
	v_add_f32_e32 v34, v34, v125
	v_sub_f32_e32 v34, v34, v137
	v_exp_f32_e32 v51, v34
	v_add_f32_e32 v34, v47, v118
	v_sub_f32_e32 v34, v34, v137
	v_exp_f32_e32 v60, v34
	v_add_f32_e32 v34, v48, v119
	v_sub_f32_e32 v34, v34, v137
	v_add_f32_e32 v42, v42, v138
	v_add_f32_e32 v43, v43, v139
	v_add_f32_e32 v44, v44, v140
	v_add_f32_e32 v45, v45, v141
	v_add_f32_e32 v46, v46, v142
	v_exp_f32_e32 v62, v34
	v_add_f32_e32 v34, v49, v120
	v_sub_f32_e32 v42, v42, v137
	v_sub_f32_e32 v43, v43, v137
	v_sub_f32_e32 v44, v44, v137
	v_sub_f32_e32 v45, v45, v137
	v_sub_f32_e32 v46, v46, v137
	v_sub_f32_e32 v34, v34, v137
	v_exp_f32_e32 v59, v42
	v_exp_f32_e32 v61, v43
	v_exp_f32_e32 v63, v44
	v_exp_f32_e32 v65, v45
	v_exp_f32_e32 v58, v46
	v_exp_f32_e32 v64, v34
	v_add_f32_e32 v35, v35, v121
	v_add_f32_e32 v36, v36, v129
	v_add_f32_e32 v37, v37, v132
	v_add_f32_e32 v41, v41, v136
	v_add_f32_e32 v38, v38, v133
	v_add_f32_e32 v39, v39, v134
	v_add_f32_e32 v40, v40, v135
	v_sub_f32_e32 v35, v35, v137
	v_sub_f32_e32 v36, v36, v137
	v_sub_f32_e32 v37, v37, v137
	v_sub_f32_e32 v34, v41, v137
	v_sub_f32_e32 v38, v38, v137
	v_sub_f32_e32 v39, v39, v137
	v_sub_f32_e32 v40, v40, v137
	v_exp_f32_e32 v53, v35
	v_exp_f32_e32 v55, v36
	v_exp_f32_e32 v57, v37
	v_exp_f32_e32 v56, v34
	v_pk_add_f32 v[34:35], v[58:59], v[60:61]
	v_pk_add_f32 v[36:37], v[62:63], v[64:65]
	v_exp_f32_e32 v50, v38
	v_exp_f32_e32 v52, v39
	v_exp_f32_e32 v54, v40
	v_pk_add_f32 v[48:49], v[34:35], v[36:37]
	v_cvt_pk_bf16_f32 v36, v51, v53
	v_cvt_pk_bf16_f32 v37, v55, v57
	v_cvt_pk_bf16_f32 v38, v50, v52
	v_cvt_pk_bf16_f32 v39, v54, v56
	s_nop 1
	ds_read2_b64 v[40:43], v145 offset0:24 offset1:26
	v_cndmask_b32_e32 v35, v94, v115, vcc
	v_cndmask_b32_e32 v34, v95, v94, vcc
	v_pk_add_f32 v[44:45], v[50:51], v[52:53]
	v_pk_add_f32 v[46:47], v[54:55], v[56:57]
	v_pk_add_f32 v[34:35], v[92:93], v[34:35]
	v_pk_add_f32 v[92:93], v[44:45], v[46:47]
	ds_read2_b64 v[44:47], v146 offset0:88 offset1:90
	v_add_f32_e32 v51, v51, v101
	s_waitcnt lgkmcnt(1)
	v_mfma_f32_32x32x16_bf16 v[2:17], v[40:43], v[36:39], v[2:17]
	v_add_f32_e32 v40, v53, v51
	v_add_f32_e32 v40, v55, v40
	ds_bpermute_b32 v100, v205, v57
	ds_bpermute_b32 v94, v205, v56
	v_add_f32_e32 v40, v57, v40
	v_add_f32_e32 v40, v50, v40
	ds_bpermute_b32 v50, v205, v65
	ds_bpermute_b32 v51, v205, v64
	v_add_f32_e32 v40, v52, v40
	s_waitcnt lgkmcnt(4)
	v_mfma_f32_32x32x16_bf16 v[18:33], v[44:47], v[36:39], v[18:33]
	s_waitcnt lgkmcnt(3)
	v_cndmask_b32_e32 v37, v100, v95, vcc
	s_waitcnt lgkmcnt(2)
	v_cndmask_b32_e32 v36, v94, v100, vcc
	v_add_f32_e32 v40, v54, v40
	v_pk_add_f32 v[38:39], v[92:93], v[36:37]
	s_waitcnt lgkmcnt(1)
	v_cndmask_b32_e32 v37, v50, v94, vcc
	s_waitcnt lgkmcnt(0)
	v_cndmask_b32_e32 v36, v51, v50, vcc
	v_add_f32_e32 v52, v56, v40
	v_cvt_pk_bf16_f32 v40, v59, v61
	v_cvt_pk_bf16_f32 v41, v63, v65
	v_cvt_pk_bf16_f32 v42, v58, v60
	v_cvt_pk_bf16_f32 v43, v62, v64
	s_nop 1
	ds_read2_b64 v[44:47], v145 offset0:28 offset1:30
	v_pk_add_f32 v[36:37], v[48:49], v[36:37]
	ds_read2_b64 v[48:51], v146 offset0:92 offset1:94
	s_waitcnt lgkmcnt(1)
	v_mfma_f32_32x32x16_bf16 v[2:17], v[44:47], v[40:43], v[2:17]
	v_add_f32_e32 v44, v59, v52
	v_add_f32_e32 v44, v61, v44
	v_add_f32_e32 v44, v63, v44
	v_add_f32_e32 v44, v65, v44
	v_add_f32_e32 v44, v58, v44
	v_add_f32_e32 v44, v60, v44
	v_add_f32_e32 v44, v62, v44
	s_waitcnt lgkmcnt(0)
	v_mfma_f32_32x32x16_bf16 v[18:33], v[48:51], v[40:43], v[18:33]
	v_add_f32_e32 v40, v64, v44
	ds_bpermute_b32 v41, v205, v40
	v_mov_b32_e32 v217, 0
	s_waitcnt lgkmcnt(0)
	v_add_f32_e32 v40, v40, v41
	v_div_scale_f32 v41, s[10:11], v40, v40, 1.0
	v_rcp_f32_e32 v42, v41
	v_div_scale_f32 v43, vcc, 1.0, v40, 1.0
	v_fma_f32 v44, -v41, v42, 1.0
	v_fmac_f32_e32 v42, v44, v42
	v_mul_f32_e32 v44, v43, v42
	v_fma_f32 v45, -v41, v44, v43
	v_fmac_f32_e32 v44, v45, v42
	v_fma_f32 v41, -v41, v44, v43
	v_div_fmas_f32 v41, v41, v42, v44
	v_div_fixup_f32 v41, v41, v40, 1.0
	v_cmp_lt_f32_e32 vcc, 0, v40
	s_nop 1
	v_cndmask_b32_e32 v40, 0, v41, vcc
	v_pk_mul_f32 v[42:43], v[80:81], v[40:41] op_sel_hi:[1,0]
	v_pk_mul_f32 v[44:45], v[84:85], v[40:41] op_sel_hi:[1,0]
	v_pk_mul_f32 v[46:47], v[86:87], v[40:41] op_sel_hi:[1,0]
	v_pk_mul_f32 v[48:49], v[88:89], v[40:41] op_sel_hi:[1,0]
	v_pk_mul_f32 v[50:51], v[90:91], v[40:41] op_sel_hi:[1,0]
	v_pk_mul_f32 v[52:53], v[34:35], v[40:41] op_sel_hi:[1,0]
	v_pk_mul_f32 v[54:55], v[38:39], v[40:41] op_sel_hi:[1,0]
	v_pk_mul_f32 v[56:57], v[36:37], v[40:41] op_sel_hi:[1,0]
	v_mul_f32_e32 v41, v122, v40
	v_mul_f32_e32 v2, v2, v41
	v_mul_f32_e32 v3, v3, v41
	v_mul_f32_e32 v18, v18, v41
	ds_write2st64_b32 v203, v2, v3 offset0:212 offset1:213
	v_mul_f32_e32 v2, v19, v41
	ds_write2st64_b32 v203, v18, v2 offset0:228 offset1:229
	v_mul_f32_e32 v2, v4, v41
	v_mul_f32_e32 v4, v5, v41
	v_mul_f32_e32 v3, v20, v41
	ds_write2st64_b32 v203, v2, v4 offset0:214 offset1:215
	v_mul_f32_e32 v2, v21, v41
	ds_write2st64_b32 v203, v3, v2 offset0:230 offset1:231
	v_mul_f32_e32 v2, v6, v41
	v_mul_f32_e32 v4, v7, v41
	v_mul_f32_e32 v3, v22, v41
	ds_write2st64_b32 v203, v2, v4 offset0:216 offset1:217
	v_mul_f32_e32 v2, v23, v41
	ds_write2st64_b32 v203, v3, v2 offset0:232 offset1:233
	v_mul_f32_e32 v2, v8, v41
	v_mul_f32_e32 v4, v9, v41
	v_mul_f32_e32 v3, v24, v41
	ds_write2st64_b32 v203, v2, v4 offset0:218 offset1:219
	v_mul_f32_e32 v2, v25, v41
	ds_write2st64_b32 v203, v3, v2 offset0:234 offset1:235
	v_mul_f32_e32 v2, v10, v41
	v_mul_f32_e32 v4, v11, v41
	v_mul_f32_e32 v3, v26, v41
	ds_write2st64_b32 v203, v2, v4 offset0:220 offset1:221
	v_mul_f32_e32 v2, v27, v41
	ds_write2st64_b32 v203, v3, v2 offset0:236 offset1:237
	v_mul_f32_e32 v2, v12, v41
	v_mul_f32_e32 v4, v13, v41
	v_mul_f32_e32 v3, v28, v41
	ds_write2st64_b32 v203, v2, v4 offset0:222 offset1:223
	v_mul_f32_e32 v2, v29, v41
	ds_write2st64_b32 v203, v3, v2 offset0:238 offset1:239
	v_mul_f32_e32 v2, v14, v41
	v_mul_f32_e32 v4, v15, v41
	v_mul_f32_e32 v3, v30, v41
	ds_write2st64_b32 v203, v2, v4 offset0:224 offset1:225
	v_mul_f32_e32 v2, v31, v41
	ds_write2st64_b32 v203, v3, v2 offset0:240 offset1:241
	ds_bpermute_b32 v3, v99, v43
	ds_bpermute_b32 v2, v99, v42
	v_mul_f32_e32 v4, v16, v41
	v_mul_f32_e32 v5, v17, v41
	ds_write2st64_b32 v203, v4, v5 offset0:226 offset1:227
	ds_bpermute_b32 v7, v99, v45
	s_waitcnt lgkmcnt(2)
; __device__ __forceinline__ void nsa_unit(const Frame& F, int plane, int qt) {
;     ...
; #pragma unroll
;         for (int k = 0; k < 16; ++k) { imp[k] += __shfl_xor(imp[k], 1); imp[k] += __shfl_xor(imp[k], 2);
;             const int jb = 2 * k + h; imp[k] = (jb == 0 || jb == cur) ? 1e9f : (jb <= cur ? imp[k] : -1e9f); }
	v_pk_fma_f32 v[2:3], v[80:81], v[40:41], v[2:3] op_sel_hi:[1,0,1]
	ds_bpermute_b32 v5, v98, v3
	ds_bpermute_b32 v4, v98, v2
	ds_bpermute_b32 v6, v99, v44
	v_mul_f32_e32 v8, v32, v41
	v_mul_f32_e32 v9, v33, v41
	ds_write2st64_b32 v203, v8, v9 offset0:242 offset1:243
	s_waitcnt lgkmcnt(2)
	v_pk_add_f32 v[2:3], v[2:3], v[4:5]
	s_waitcnt lgkmcnt(1)
	v_pk_fma_f32 v[4:5], v[84:85], v[40:41], v[6:7] op_sel_hi:[1,0,1]
	ds_bpermute_b32 v7, v98, v5
	ds_bpermute_b32 v6, v98, v4
	v_cmp_ge_u32_e32 vcc, s8, v68
	s_waitcnt lgkmcnt(0)
	v_pk_add_f32 v[4:5], v[4:5], v[6:7]
	ds_bpermute_b32 v7, v99, v47
	ds_bpermute_b32 v6, v99, v46
	v_cndmask_b32_e32 v2, v235, v2, vcc
	v_cmp_ge_u32_e32 vcc, s8, v1
	s_waitcnt lgkmcnt(0)
	v_pk_fma_f32 v[6:7], v[86:87], v[40:41], v[6:7] op_sel_hi:[1,0,1]
	ds_bpermute_b32 v9, v98, v7
	ds_bpermute_b32 v8, v98, v6
	v_cndmask_b32_e32 v3, v235, v3, vcc
	v_cmp_ne_u32_e32 vcc, s8, v68
	v_cndmask_b32_e64 v3, v3, v236, s[0:1]
	s_waitcnt lgkmcnt(0)
	v_pk_add_f32 v[6:7], v[6:7], v[8:9]
	ds_bpermute_b32 v9, v99, v49
	ds_bpermute_b32 v8, v99, v48
	v_cndmask_b32_e32 v2, v236, v2, vcc
	v_cmp_ge_u32_e32 vcc, s8, v82
	s_waitcnt lgkmcnt(0)
	v_pk_fma_f32 v[8:9], v[88:89], v[40:41], v[8:9] op_sel_hi:[1,0,1]
	ds_bpermute_b32 v11, v98, v9
	ds_bpermute_b32 v10, v98, v8
	v_cndmask_b32_e32 v4, v235, v4, vcc
	v_cmp_ge_u32_e32 vcc, s8, v79
	s_waitcnt lgkmcnt(0)
	v_pk_add_f32 v[8:9], v[8:9], v[10:11]
	ds_bpermute_b32 v11, v99, v51
	ds_bpermute_b32 v10, v99, v50
	v_cndmask_b32_e32 v5, v235, v5, vcc
	v_cmp_ne_u32_e32 vcc, s8, v79
	s_waitcnt lgkmcnt(0)
	v_pk_fma_f32 v[10:11], v[90:91], v[40:41], v[10:11] op_sel_hi:[1,0,1]
	ds_bpermute_b32 v13, v98, v11
	ds_bpermute_b32 v12, v98, v10
	v_cndmask_b32_e32 v5, v236, v5, vcc
	v_cmp_ne_u32_e32 vcc, s8, v82
	s_waitcnt lgkmcnt(0)
	v_pk_add_f32 v[10:11], v[10:11], v[12:13]
	ds_bpermute_b32 v13, v99, v53
	ds_bpermute_b32 v12, v99, v52
	v_cndmask_b32_e32 v4, v236, v4, vcc
	v_cmp_ge_u32_e32 vcc, s8, v78
	s_waitcnt lgkmcnt(0)
	v_pk_fma_f32 v[12:13], v[34:35], v[40:41], v[12:13] op_sel_hi:[1,0,1]
	ds_bpermute_b32 v15, v98, v13
	ds_bpermute_b32 v14, v98, v12
	v_cndmask_b32_e32 v6, v235, v6, vcc
	v_cmp_ge_u32_e32 vcc, s8, v77
	s_waitcnt lgkmcnt(0)
	v_pk_add_f32 v[12:13], v[12:13], v[14:15]
	ds_bpermute_b32 v15, v99, v55
	ds_bpermute_b32 v14, v99, v54
	v_cndmask_b32_e32 v7, v235, v7, vcc
	v_cmp_ne_u32_e32 vcc, s8, v77
	s_waitcnt lgkmcnt(0)
	v_pk_fma_f32 v[14:15], v[38:39], v[40:41], v[14:15] op_sel_hi:[1,0,1]
	v_cndmask_b32_e32 v7, v236, v7, vcc
	v_cmp_ne_u32_e32 vcc, s8, v78
	ds_bpermute_b32 v17, v98, v15
	ds_bpermute_b32 v16, v98, v14
	v_cndmask_b32_e32 v6, v236, v6, vcc
	v_cmp_ge_u32_e32 vcc, s8, v76
	s_waitcnt lgkmcnt(0)
	v_pk_add_f32 v[14:15], v[14:15], v[16:17]
	v_cndmask_b32_e32 v8, v235, v8, vcc
	v_cmp_ge_u32_e32 vcc, s8, v75
	ds_bpermute_b32 v17, v99, v57
	ds_bpermute_b32 v16, v99, v56
	v_cndmask_b32_e32 v9, v235, v9, vcc
	v_cmp_ne_u32_e32 vcc, s8, v75
	s_waitcnt lgkmcnt(0)
	v_pk_fma_f32 v[16:17], v[36:37], v[40:41], v[16:17] op_sel_hi:[1,0,1]
	v_cndmask_b32_e32 v9, v236, v9, vcc
	v_cmp_ne_u32_e32 vcc, s8, v76
	ds_bpermute_b32 v19, v98, v17
	ds_bpermute_b32 v18, v98, v16
	v_cndmask_b32_e32 v8, v236, v8, vcc
	v_cmp_ge_u32_e32 vcc, s8, v74
	s_waitcnt lgkmcnt(0)
	v_pk_add_f32 v[18:19], v[16:17], v[18:19]
	v_cndmask_b32_e32 v10, v235, v10, vcc
	v_cmp_ge_u32_e32 vcc, s8, v73
	v_or_b32_e32 v16, 30, v1
	v_or_b32_e32 v17, 28, v1
	v_cndmask_b32_e32 v11, v235, v11, vcc
	v_cmp_ne_u32_e32 vcc, s8, v73
	s_nop 1
	v_cndmask_b32_e32 v11, v236, v11, vcc
	v_cmp_ne_u32_e32 vcc, s8, v74
	s_nop 1
	v_cndmask_b32_e32 v10, v236, v10, vcc
	v_cmp_ge_u32_e32 vcc, s8, v72
	s_nop 1
	v_cndmask_b32_e32 v12, v235, v12, vcc
	v_cmp_ge_u32_e32 vcc, s8, v71
	s_nop 1
	v_cndmask_b32_e32 v13, v235, v13, vcc
	v_cmp_ne_u32_e32 vcc, s8, v71
	s_nop 1
	v_cndmask_b32_e32 v13, v236, v13, vcc
	v_cmp_ne_u32_e32 vcc, s8, v72
	s_nop 1
	v_cndmask_b32_e32 v12, v236, v12, vcc
	v_cmp_ge_u32_e32 vcc, s8, v70
	s_nop 1
	v_cndmask_b32_e32 v14, v235, v14, vcc
	v_cmp_ge_u32_e32 vcc, s8, v69
	s_nop 1
	v_cndmask_b32_e32 v15, v235, v15, vcc
	v_cmp_ne_u32_e32 vcc, s8, v69
	s_nop 1
	v_cndmask_b32_e32 v15, v236, v15, vcc
	v_cmp_ne_u32_e32 vcc, s8, v70
	s_nop 1
	v_cndmask_b32_e32 v14, v236, v14, vcc
	v_cmp_ge_u32_e32 vcc, s8, v16
	s_nop 1
	v_cndmask_b32_e32 v18, v235, v18, vcc
	v_cmp_ge_u32_e32 vcc, s8, v17
	s_nop 1
	v_cndmask_b32_e32 v19, v235, v19, vcc
	v_cmp_ne_u32_e32 vcc, s8, v17
	s_nop 1
	v_cndmask_b32_e32 v19, v236, v19, vcc
	v_cmp_ne_u32_e32 vcc, s8, v16
	s_nop 1
	v_cndmask_b32_e32 v18, v236, v18, vcc
; #define LDS_BARRIER() do { asm volatile("s_waitcnt lgkmcnt(0)" ::: "memory"); __builtin_amdgcn_s_barrier(); asm volatile("" ::: "memory"); } while (0)
; template <int BR>
; __device__ __forceinline__ void nsa_branch(const Frame& F, int plane, int qt, int t, int r, int h, unsigned selmask, const bf16x8 (&qr)[4], float gate) {
;     ...
;     nsa_kv_load(c, c.jlo, kreg, vreg);
;     LDS_BARRIER();
;     nsa_kv_write(L, 0, c, kreg, vreg);
;     if (nblk > 1) nsa_kv_load(c, c.jlo + 1, kreg, vreg);
;     LDS_BARRIER();
;     if (nblk > 1) { nsa_kv_write(L, NL_SLOT, c, kreg, vreg); if (nblk > 2) nsa_kv_load(c, c.jlo + 2, kreg, vreg); }
; __device__ __forceinline__ void nsa_unit(const Frame& F, int plane, int qt) {
;     ...
; #pragma unroll 1
;         for (int round = 0; round < 8; ++round) {
;             float bv = imp[0]; int bj = h;
; #pragma unroll
;             for (int k = 1; k < 16; ++k) { const bool tk = imp[k] > bv; bv = tk ? imp[k] : bv; bj = tk ? 2 * k + h : bj; }
;             const float ov = __shfl_xor(bv, 32); const int oj = __shfl_xor(bj, 32);
;             const bool take = (ov > bv) || (ov == bv && oj < bj);
;             bj = take ? oj : bj;
;             selmask |= 1u << bj;
; #pragma unroll
;             for (int k = 0; k < 16; ++k) imp[k] = (2 * k + h == bj) ? -INFINITY : imp[k];
;         }
;     }
;     bf16x8 qr[4];
; #pragma unroll
;     for (int ks = 0; ks < 4; ++ks) qr[ks] = *(const bf16x8*)((const bf16*)(F.ws + WS_NQRB) + qoff + 16 * ks);
.LBB0_1752:
	v_cmp_gt_f32_e32 vcc, v2, v3
	s_add_i32 s14, s14, -1
	s_cmp_eq_u32 s14, 0
	v_cndmask_b32_e32 v20, v3, v2, vcc
	v_cndmask_b32_e32 v21, v1, v68, vcc
	v_cmp_gt_f32_e32 vcc, v5, v20
	s_nop 1
	v_cndmask_b32_e32 v20, v20, v5, vcc
	v_cndmask_b32_e32 v21, v21, v79, vcc
	v_cmp_gt_f32_e32 vcc, v4, v20
	s_nop 1
	v_cndmask_b32_e32 v20, v20, v4, vcc
	v_cndmask_b32_e32 v21, v21, v82, vcc
	v_cmp_gt_f32_e32 vcc, v7, v20
	s_nop 1
	v_cndmask_b32_e32 v20, v20, v7, vcc
	v_cndmask_b32_e32 v21, v21, v77, vcc
	v_cmp_gt_f32_e32 vcc, v6, v20
	s_nop 1
	v_cndmask_b32_e32 v20, v20, v6, vcc
	v_cndmask_b32_e32 v21, v21, v78, vcc
	v_cmp_gt_f32_e32 vcc, v9, v20
	s_nop 1
	v_cndmask_b32_e32 v20, v20, v9, vcc
	v_cndmask_b32_e32 v21, v21, v75, vcc
	v_cmp_gt_f32_e32 vcc, v8, v20
	s_nop 1
	v_cndmask_b32_e32 v20, v20, v8, vcc
	v_cndmask_b32_e32 v21, v21, v76, vcc
	v_cmp_gt_f32_e32 vcc, v11, v20
	s_nop 1
	v_cndmask_b32_e32 v20, v20, v11, vcc
	v_cndmask_b32_e32 v21, v21, v73, vcc
	v_cmp_gt_f32_e32 vcc, v10, v20
	s_nop 1
	v_cndmask_b32_e32 v20, v20, v10, vcc
	v_cndmask_b32_e32 v21, v21, v74, vcc
	v_cmp_gt_f32_e32 vcc, v13, v20
	s_nop 1
	v_cndmask_b32_e32 v20, v20, v13, vcc
	v_cndmask_b32_e32 v21, v21, v71, vcc
	v_cmp_gt_f32_e32 vcc, v12, v20
	s_nop 1
	v_cndmask_b32_e32 v20, v20, v12, vcc
	v_cndmask_b32_e32 v21, v21, v72, vcc
	v_cmp_gt_f32_e32 vcc, v15, v20
	s_nop 1
	v_cndmask_b32_e32 v20, v20, v15, vcc
	v_cndmask_b32_e32 v21, v21, v69, vcc
	v_cmp_gt_f32_e32 vcc, v14, v20
	s_nop 1
	v_cndmask_b32_e32 v20, v20, v14, vcc
	v_cndmask_b32_e32 v21, v21, v70, vcc
	v_cmp_gt_f32_e32 vcc, v19, v20
	s_nop 1
	v_cndmask_b32_e32 v20, v20, v19, vcc
	v_cndmask_b32_e32 v21, v21, v17, vcc
	v_cmp_gt_f32_e32 vcc, v18, v20
	s_nop 1
	v_cndmask_b32_e32 v20, v20, v18, vcc
	v_cndmask_b32_e32 v21, v21, v16, vcc
	ds_bpermute_b32 v22, v205, v21
	ds_bpermute_b32 v23, v205, v20
	s_waitcnt lgkmcnt(1)
	v_min_i32_e32 v24, v22, v21
	s_waitcnt lgkmcnt(0)
	v_cmp_eq_f32_e32 vcc, v20, v23
	s_nop 1
	v_cndmask_b32_e32 v21, v21, v24, vcc
	v_cmp_lt_f32_e32 vcc, v20, v23
	s_nop 1
	v_cndmask_b32_e32 v20, v21, v22, vcc
	v_cmp_ne_u32_e32 vcc, v1, v20
	v_lshl_or_b32 v217, 1, v20, v217
	s_nop 0
	v_cndmask_b32_e32 v3, v237, v3, vcc
	v_cmp_ne_u32_e32 vcc, v68, v20
	s_nop 1
	v_cndmask_b32_e32 v2, v237, v2, vcc
	v_cmp_ne_u32_e32 vcc, v79, v20
	s_nop 1
	v_cndmask_b32_e32 v5, v237, v5, vcc
	v_cmp_ne_u32_e32 vcc, v82, v20
	s_nop 1
	v_cndmask_b32_e32 v4, v237, v4, vcc
	v_cmp_ne_u32_e32 vcc, v77, v20
	s_nop 1
	v_cndmask_b32_e32 v7, v237, v7, vcc
	v_cmp_ne_u32_e32 vcc, v78, v20
	s_nop 1
	v_cndmask_b32_e32 v6, v237, v6, vcc
	v_cmp_ne_u32_e32 vcc, v75, v20
	s_nop 1
	v_cndmask_b32_e32 v9, v237, v9, vcc
	v_cmp_ne_u32_e32 vcc, v76, v20
	s_nop 1
	v_cndmask_b32_e32 v8, v237, v8, vcc
	v_cmp_ne_u32_e32 vcc, v73, v20
	s_nop 1
	v_cndmask_b32_e32 v11, v237, v11, vcc
	v_cmp_ne_u32_e32 vcc, v74, v20
	s_nop 1
	v_cndmask_b32_e32 v10, v237, v10, vcc
	v_cmp_ne_u32_e32 vcc, v71, v20
	s_nop 1
	v_cndmask_b32_e32 v13, v237, v13, vcc
	v_cmp_ne_u32_e32 vcc, v72, v20
	s_nop 1
	v_cndmask_b32_e32 v12, v237, v12, vcc
	v_cmp_ne_u32_e32 vcc, v69, v20
	s_nop 1
	v_cndmask_b32_e32 v15, v237, v15, vcc
	v_cmp_ne_u32_e32 vcc, v70, v20
	s_nop 1
	v_cndmask_b32_e32 v14, v237, v14, vcc
	v_cmp_ne_u32_e32 vcc, v17, v20
	s_nop 1
	v_cndmask_b32_e32 v19, v237, v19, vcc
	v_cmp_ne_u32_e32 vcc, v16, v20
	s_nop 1
	v_cndmask_b32_e32 v18, v237, v18, vcc
	s_cbranch_scc0 .LBB0_1752
	s_mov_b64 s[0:1], 0x6c800000
	s_lshl_b32 s9, s9, 18
	v_lshl_add_u64 v[2:3], v[66:67], 0, s[0:1]
	s_add_u32 s0, s28, s9
	s_addc_u32 s1, s29, 0
	v_add_co_u32_e32 v4, vcc, 0x6c800000, v66
	s_add_u32 s10, s0, 0x6e000000
	s_nop 0
	v_addc_co_u32_e32 v5, vcc, 0, v67, vcc
	s_addc_u32 s11, s1, 0
	v_lshlrev_b64 v[34:35], 7, v[130:131]
	global_load_dwordx4 v[98:101], v[4:5], off nt
	global_load_dwordx4 v[102:105], v[2:3], off offset:32 nt
	global_load_dwordx4 v[106:109], v[2:3], off offset:64 nt
	global_load_dwordx4 v[110:113], v[2:3], off offset:96 nt
	v_lshl_add_u64 v[2:3], s[10:11], 0, v[34:35]
	v_lshl_add_u64 v[4:5], v[2:3], 0, v[198:199]
	v_lshlrev_b64 v[162:163], 12, v[130:131]
	v_lshlrev_b32_e32 v8, 3, v114
	global_load_dwordx4 v[114:117], v[4:5], off
	v_lshl_add_u64 v[4:5], s[0:1], 0, v[162:163]
	v_lshl_add_u64 v[6:7], v[4:5], 0, v[198:199]
	s_mov_b64 s[0:1], 0x6e400000
	v_lshl_add_u64 v[4:5], v[6:7], 0, s[0:1]
	s_mov_b32 s0, 0x6e400000
	v_add_co_u32_e32 v6, vcc, s0, v6
	v_mul_lo_u32 v207, v130, s3
	s_nop 0
	v_addc_co_u32_e32 v7, vcc, 0, v7, vcc
	global_load_dwordx4 v[118:121], v[6:7], off
	s_waitcnt lgkmcnt(0)
	s_barrier
	v_add_u32_e32 v1, 0, v207
	v_lshlrev_b32_e32 v6, 3, v130
	s_cmp_lg_u32 s8, 0
	v_add_u32_e32 v212, v1, v198
	v_sub_u32_e32 v1, v1, v6
	s_cselect_b64 s[0:1], -1, 0
	v_add3_u32 v213, v1, v198, s13
	s_and_b64 vcc, exec, s[0:1]
	v_lshlrev_b32_e32 v132, 1, v8
	s_waitcnt vmcnt(1)
	ds_write_b128 v212, v[114:117]
	s_waitcnt vmcnt(0)
	ds_write2_b64 v213, v[118:119], v[120:121] offset1:1
	s_cbranch_vccz .LBB0_1755
	v_mov_b32_e32 v133, v199
	v_lshl_add_u64 v[6:7], v[2:3], 0, v[132:133]
	v_add_co_u32_e32 v6, vcc, 0x2000, v6
	s_nop 1
	v_addc_co_u32_e32 v7, vcc, 0, v7, vcc
	global_load_dwordx4 v[114:117], v[6:7], off
	global_load_dwordx4 v[118:121], v[4:5], off offset:128
